# no vmcnt0 drain in GEMM unit headers + skinny GEMM loads hoisted (ao/down)
# baseline (speedup 1.0000x reference)
.LBB0_265:
	s_ashr_i32 s75, s74, 31
	s_lshl_b64 s[0:1], s[74:75], 19
	s_add_u32 s76, s26, s0
	s_addc_u32 s77, s27, s1
	s_and_b64 s[0:1], s[38:39], exec
	s_cselect_b32 s0, s77, s23
	s_cselect_b32 s1, s76, s22
	s_ashr_i32 s73, s72, 31
	s_lshl_b64 s[2:3], s[72:73], 19
	s_add_u32 s78, s50, s2
	s_addc_u32 s79, s51, s3
	s_and_b64 s[2:3], s[38:39], exec
	s_cselect_b32 s9, s79, s21
	s_cselect_b32 s10, s78, s20
	s_add_u32 s2, s22, 0x40080
	s_addc_u32 s3, s23, 0
	s_add_u32 s11, s20, 0x100
	v_mov_b32_e32 v4, 0
	s_addc_u32 s12, s21, 0
	s_mov_b32 s17, -2
	v_mov_b32_e32 v5, v4
	v_mov_b32_e32 v6, v4
	v_mov_b32_e32 v7, v4
	v_mov_b32_e32 v8, v4
	v_mov_b32_e32 v9, v4
	v_mov_b32_e32 v10, v4
	v_mov_b32_e32 v11, v4
	v_mov_b32_e32 v20, v4
	v_mov_b32_e32 v21, v4
	v_mov_b32_e32 v22, v4
	v_mov_b32_e32 v23, v4
	v_mov_b32_e32 v24, v4
	v_mov_b32_e32 v25, v4
	v_mov_b32_e32 v26, v4
	v_mov_b32_e32 v27, v4
	v_mov_b32_e32 v36, v4
	v_mov_b32_e32 v37, v4
	v_mov_b32_e32 v38, v4
	v_mov_b32_e32 v39, v4
	v_mov_b32_e32 v40, v4
	v_mov_b32_e32 v41, v4
	v_mov_b32_e32 v42, v4
	v_mov_b32_e32 v43, v4
	v_mov_b32_e32 v52, v4
	v_mov_b32_e32 v53, v4
	v_mov_b32_e32 v54, v4
	v_mov_b32_e32 v55, v4
	v_mov_b32_e32 v56, v4
	v_mov_b32_e32 v57, v4
	v_mov_b32_e32 v58, v4
	v_mov_b32_e32 v59, v4
	v_mov_b32_e32 v12, v4
	v_mov_b32_e32 v13, v4
	v_mov_b32_e32 v14, v4
	v_mov_b32_e32 v15, v4
	v_mov_b32_e32 v16, v4
	v_mov_b32_e32 v17, v4
	v_mov_b32_e32 v18, v4
	v_mov_b32_e32 v19, v4
	v_mov_b32_e32 v28, v4
	v_mov_b32_e32 v29, v4
	v_mov_b32_e32 v30, v4
	v_mov_b32_e32 v31, v4
	v_mov_b32_e32 v32, v4
	v_mov_b32_e32 v33, v4
	v_mov_b32_e32 v34, v4
	v_mov_b32_e32 v35, v4
	v_mov_b32_e32 v44, v4
	v_mov_b32_e32 v45, v4
	v_mov_b32_e32 v46, v4
	v_mov_b32_e32 v47, v4
	v_mov_b32_e32 v48, v4
	v_mov_b32_e32 v49, v4
	v_mov_b32_e32 v50, v4
	v_mov_b32_e32 v51, v4
	v_mov_b32_e32 v60, v4
	v_mov_b32_e32 v61, v4
	v_mov_b32_e32 v62, v4
	v_mov_b32_e32 v63, v4
	v_mov_b32_e32 v64, v4
	v_mov_b32_e32 v65, v4
	v_mov_b32_e32 v66, v4
	v_mov_b32_e32 v67, v4
	v_mov_b32_e32 v68, v4
	v_mov_b32_e32 v69, v4
	v_mov_b32_e32 v70, v4
	v_mov_b32_e32 v71, v4
	v_mov_b32_e32 v72, v4
	v_mov_b32_e32 v73, v4
	v_mov_b32_e32 v74, v4
	v_mov_b32_e32 v75, v4
	v_mov_b32_e32 v84, v4
	v_mov_b32_e32 v85, v4
	v_mov_b32_e32 v86, v4
	v_mov_b32_e32 v87, v4
	v_mov_b32_e32 v88, v4
	v_mov_b32_e32 v89, v4
	v_mov_b32_e32 v90, v4
	v_mov_b32_e32 v91, v4
	v_mov_b32_e32 v100, v4
	v_mov_b32_e32 v101, v4
	v_mov_b32_e32 v102, v4
	v_mov_b32_e32 v103, v4
	v_mov_b32_e32 v104, v4
	v_mov_b32_e32 v105, v4
	v_mov_b32_e32 v106, v4
	v_mov_b32_e32 v107, v4
	v_mov_b32_e32 v116, v4
	v_mov_b32_e32 v117, v4
	v_mov_b32_e32 v118, v4
	v_mov_b32_e32 v119, v4
	v_mov_b32_e32 v120, v4
	v_mov_b32_e32 v121, v4
	v_mov_b32_e32 v122, v4
	v_mov_b32_e32 v123, v4
	v_mov_b32_e32 v76, v4
	v_mov_b32_e32 v77, v4
	v_mov_b32_e32 v78, v4
	v_mov_b32_e32 v79, v4
	v_mov_b32_e32 v80, v4
	v_mov_b32_e32 v81, v4
	v_mov_b32_e32 v82, v4
	v_mov_b32_e32 v83, v4
	v_mov_b32_e32 v92, v4
	v_mov_b32_e32 v93, v4
	v_mov_b32_e32 v94, v4
	v_mov_b32_e32 v95, v4
	v_mov_b32_e32 v96, v4
	v_mov_b32_e32 v97, v4
	v_mov_b32_e32 v98, v4
	v_mov_b32_e32 v99, v4
	v_mov_b32_e32 v108, v4
	v_mov_b32_e32 v109, v4
	v_mov_b32_e32 v110, v4
	v_mov_b32_e32 v111, v4
	v_mov_b32_e32 v112, v4
	v_mov_b32_e32 v113, v4
	v_mov_b32_e32 v114, v4
	v_mov_b32_e32 v115, v4
	v_mov_b32_e32 v124, v4
	v_mov_b32_e32 v125, v4
	v_mov_b32_e32 v126, v4
	v_mov_b32_e32 v127, v4
	v_mov_b32_e32 v128, v4
	v_mov_b32_e32 v129, v4
	v_mov_b32_e32 v130, v4
	v_mov_b32_e32 v131, v4

.LBB0_1003:
	s_ashr_i32 s21, s20, 31
	s_lshl_b64 s[0:1], s[20:21], 19
	s_add_u32 s36, s4, s0
	s_addc_u32 s37, s5, s1
	s_and_b64 s[0:1], s[28:29], exec
	s_cselect_b32 s0, s37, s39
	s_cselect_b32 s1, s36, s38
	s_ashr_i32 s23, s22, 31
	s_lshl_b64 s[34:35], s[22:23], 19
	s_add_u32 s34, s8, s34
	s_addc_u32 s35, s9, s35
	s_and_b64 s[42:43], s[28:29], exec
	s_cselect_b32 s21, s35, s41
	s_cselect_b32 s23, s34, s40
	s_add_u32 s38, s38, 0x40080
	s_addc_u32 s39, s39, 0
	s_add_u32 s48, s40, 0x100
	v_mov_b32_e32 v4, 0
	s_addc_u32 s49, s41, 0
	s_mov_b32 s50, -2
	v_mov_b32_e32 v5, v4
	v_mov_b32_e32 v6, v4
	v_mov_b32_e32 v7, v4
	v_mov_b32_e32 v8, v4
	v_mov_b32_e32 v9, v4
	v_mov_b32_e32 v10, v4
	v_mov_b32_e32 v11, v4
	v_mov_b32_e32 v12, v4
	v_mov_b32_e32 v13, v4
	v_mov_b32_e32 v14, v4
	v_mov_b32_e32 v15, v4
	v_mov_b32_e32 v16, v4
	v_mov_b32_e32 v17, v4
	v_mov_b32_e32 v18, v4
	v_mov_b32_e32 v19, v4
	v_mov_b32_e32 v28, v4
	v_mov_b32_e32 v29, v4
	v_mov_b32_e32 v30, v4
	v_mov_b32_e32 v31, v4
	v_mov_b32_e32 v32, v4
	v_mov_b32_e32 v33, v4
	v_mov_b32_e32 v34, v4
	v_mov_b32_e32 v35, v4
	v_mov_b32_e32 v44, v4
	v_mov_b32_e32 v45, v4
	v_mov_b32_e32 v46, v4
	v_mov_b32_e32 v47, v4
	v_mov_b32_e32 v48, v4
	v_mov_b32_e32 v49, v4
	v_mov_b32_e32 v50, v4
	v_mov_b32_e32 v51, v4
	v_mov_b32_e32 v20, v4
	v_mov_b32_e32 v21, v4
	v_mov_b32_e32 v22, v4
	v_mov_b32_e32 v23, v4
	v_mov_b32_e32 v24, v4
	v_mov_b32_e32 v25, v4
	v_mov_b32_e32 v26, v4
	v_mov_b32_e32 v27, v4
	v_mov_b32_e32 v36, v4
	v_mov_b32_e32 v37, v4
	v_mov_b32_e32 v38, v4
	v_mov_b32_e32 v39, v4
	v_mov_b32_e32 v40, v4
	v_mov_b32_e32 v41, v4
	v_mov_b32_e32 v42, v4
	v_mov_b32_e32 v43, v4
	v_mov_b32_e32 v52, v4
	v_mov_b32_e32 v53, v4
	v_mov_b32_e32 v54, v4
	v_mov_b32_e32 v55, v4
	v_mov_b32_e32 v56, v4
	v_mov_b32_e32 v57, v4
	v_mov_b32_e32 v58, v4
	v_mov_b32_e32 v59, v4
	v_mov_b32_e32 v60, v4
	v_mov_b32_e32 v61, v4
	v_mov_b32_e32 v62, v4
	v_mov_b32_e32 v63, v4
	v_mov_b32_e32 v64, v4
	v_mov_b32_e32 v65, v4
	v_mov_b32_e32 v66, v4
	v_mov_b32_e32 v67, v4
	v_mov_b32_e32 v68, v4
	v_mov_b32_e32 v69, v4
	v_mov_b32_e32 v70, v4
	v_mov_b32_e32 v71, v4
	v_mov_b32_e32 v72, v4
	v_mov_b32_e32 v73, v4
	v_mov_b32_e32 v74, v4
	v_mov_b32_e32 v75, v4
	v_mov_b32_e32 v76, v4
	v_mov_b32_e32 v77, v4
	v_mov_b32_e32 v78, v4
	v_mov_b32_e32 v79, v4
	v_mov_b32_e32 v80, v4
	v_mov_b32_e32 v81, v4
	v_mov_b32_e32 v82, v4
	v_mov_b32_e32 v83, v4
	v_mov_b32_e32 v92, v4
	v_mov_b32_e32 v93, v4
	v_mov_b32_e32 v94, v4
	v_mov_b32_e32 v95, v4
	v_mov_b32_e32 v96, v4
	v_mov_b32_e32 v97, v4
	v_mov_b32_e32 v98, v4
	v_mov_b32_e32 v99, v4
	v_mov_b32_e32 v108, v4
	v_mov_b32_e32 v109, v4
	v_mov_b32_e32 v110, v4
	v_mov_b32_e32 v111, v4
	v_mov_b32_e32 v112, v4
	v_mov_b32_e32 v113, v4
	v_mov_b32_e32 v114, v4
	v_mov_b32_e32 v115, v4
	v_mov_b32_e32 v84, v4
	v_mov_b32_e32 v85, v4
	v_mov_b32_e32 v86, v4
	v_mov_b32_e32 v87, v4
	v_mov_b32_e32 v88, v4
	v_mov_b32_e32 v89, v4
	v_mov_b32_e32 v90, v4
	v_mov_b32_e32 v91, v4
	v_mov_b32_e32 v100, v4
	v_mov_b32_e32 v101, v4
	v_mov_b32_e32 v102, v4
	v_mov_b32_e32 v103, v4
	v_mov_b32_e32 v104, v4
	v_mov_b32_e32 v105, v4
	v_mov_b32_e32 v106, v4
	v_mov_b32_e32 v107, v4
	v_mov_b32_e32 v116, v4
	v_mov_b32_e32 v117, v4
	v_mov_b32_e32 v118, v4
	v_mov_b32_e32 v119, v4
	v_mov_b32_e32 v120, v4
	v_mov_b32_e32 v121, v4
	v_mov_b32_e32 v122, v4
	v_mov_b32_e32 v123, v4
	v_mov_b32_e32 v124, v4
	v_mov_b32_e32 v125, v4
	v_mov_b32_e32 v126, v4
	v_mov_b32_e32 v127, v4
	v_mov_b32_e32 v128, v4
	v_mov_b32_e32 v129, v4
	v_mov_b32_e32 v130, v4
	v_mov_b32_e32 v131, v4

.LBB0_2429:
	s_ashr_i32 s41, s40, 31
	s_lshl_b64 s[0:1], s[40:41], 19
	s_add_u32 s42, s8, s0
	s_addc_u32 s43, s9, s1
	s_and_b64 s[0:1], s[2:3], exec
	s_cselect_b32 s0, s43, s5
	s_cselect_b32 s1, s42, s4
	s_ashr_i32 s27, s26, 31
	s_lshl_b64 s[10:11], s[26:27], 19
	s_add_u32 s44, s20, s10
	s_addc_u32 s45, s21, s11
	s_and_b64 s[10:11], s[2:3], exec
	s_cselect_b32 s10, s45, s7
	s_cselect_b32 s11, s44, s6
	s_add_u32 s4, s4, 0x40080
	s_addc_u32 s5, s5, 0
	s_add_u32 s27, s6, 0x100
	v_mov_b32_e32 v4, 0
	s_addc_u32 s41, s7, 0
	s_mov_b32 s57, -2
	v_mov_b32_e32 v5, v4
	v_mov_b32_e32 v6, v4
	v_mov_b32_e32 v7, v4
	v_mov_b32_e32 v8, v4
	v_mov_b32_e32 v9, v4
	v_mov_b32_e32 v10, v4
	v_mov_b32_e32 v11, v4
	v_mov_b32_e32 v20, v4
	v_mov_b32_e32 v21, v4
	v_mov_b32_e32 v22, v4
	v_mov_b32_e32 v23, v4
	v_mov_b32_e32 v24, v4
	v_mov_b32_e32 v25, v4
	v_mov_b32_e32 v26, v4
	v_mov_b32_e32 v27, v4
	v_mov_b32_e32 v36, v4
	v_mov_b32_e32 v37, v4
	v_mov_b32_e32 v38, v4
	v_mov_b32_e32 v39, v4
	v_mov_b32_e32 v40, v4
	v_mov_b32_e32 v41, v4
	v_mov_b32_e32 v42, v4
	v_mov_b32_e32 v43, v4
	v_mov_b32_e32 v52, v4
	v_mov_b32_e32 v53, v4
	v_mov_b32_e32 v54, v4
	v_mov_b32_e32 v55, v4
	v_mov_b32_e32 v56, v4
	v_mov_b32_e32 v57, v4
	v_mov_b32_e32 v58, v4
	v_mov_b32_e32 v59, v4
	v_mov_b32_e32 v12, v4
	v_mov_b32_e32 v13, v4
	v_mov_b32_e32 v14, v4
	v_mov_b32_e32 v15, v4
	v_mov_b32_e32 v16, v4
	v_mov_b32_e32 v17, v4
	v_mov_b32_e32 v18, v4
	v_mov_b32_e32 v19, v4
	v_mov_b32_e32 v28, v4
	v_mov_b32_e32 v29, v4
	v_mov_b32_e32 v30, v4
	v_mov_b32_e32 v31, v4
	v_mov_b32_e32 v32, v4
	v_mov_b32_e32 v33, v4
	v_mov_b32_e32 v34, v4
	v_mov_b32_e32 v35, v4
	v_mov_b32_e32 v44, v4
	v_mov_b32_e32 v45, v4
	v_mov_b32_e32 v46, v4
	v_mov_b32_e32 v47, v4
	v_mov_b32_e32 v48, v4
	v_mov_b32_e32 v49, v4
	v_mov_b32_e32 v50, v4
	v_mov_b32_e32 v51, v4
	v_mov_b32_e32 v60, v4
	v_mov_b32_e32 v61, v4
	v_mov_b32_e32 v62, v4
	v_mov_b32_e32 v63, v4
	v_mov_b32_e32 v64, v4
	v_mov_b32_e32 v65, v4
	v_mov_b32_e32 v66, v4
	v_mov_b32_e32 v67, v4
	v_mov_b32_e32 v68, v4
	v_mov_b32_e32 v69, v4
	v_mov_b32_e32 v70, v4
	v_mov_b32_e32 v71, v4
	v_mov_b32_e32 v72, v4
	v_mov_b32_e32 v73, v4
	v_mov_b32_e32 v74, v4
	v_mov_b32_e32 v75, v4
	v_mov_b32_e32 v84, v4
	v_mov_b32_e32 v85, v4
	v_mov_b32_e32 v86, v4
	v_mov_b32_e32 v87, v4
	v_mov_b32_e32 v88, v4
	v_mov_b32_e32 v89, v4
	v_mov_b32_e32 v90, v4
	v_mov_b32_e32 v91, v4
	v_mov_b32_e32 v100, v4
	v_mov_b32_e32 v101, v4
	v_mov_b32_e32 v102, v4
	v_mov_b32_e32 v103, v4
	v_mov_b32_e32 v104, v4
	v_mov_b32_e32 v105, v4
	v_mov_b32_e32 v106, v4
	v_mov_b32_e32 v107, v4
	v_mov_b32_e32 v116, v4
	v_mov_b32_e32 v117, v4
	v_mov_b32_e32 v118, v4
	v_mov_b32_e32 v119, v4
	v_mov_b32_e32 v120, v4
	v_mov_b32_e32 v121, v4
	v_mov_b32_e32 v122, v4
	v_mov_b32_e32 v123, v4
	v_mov_b32_e32 v76, v4
	v_mov_b32_e32 v77, v4
	v_mov_b32_e32 v78, v4
	v_mov_b32_e32 v79, v4
	v_mov_b32_e32 v80, v4
	v_mov_b32_e32 v81, v4
	v_mov_b32_e32 v82, v4
	v_mov_b32_e32 v83, v4
	v_mov_b32_e32 v92, v4
	v_mov_b32_e32 v93, v4
	v_mov_b32_e32 v94, v4
	v_mov_b32_e32 v95, v4
	v_mov_b32_e32 v96, v4
	v_mov_b32_e32 v97, v4
	v_mov_b32_e32 v98, v4
	v_mov_b32_e32 v99, v4
	v_mov_b32_e32 v108, v4
	v_mov_b32_e32 v109, v4
	v_mov_b32_e32 v110, v4
	v_mov_b32_e32 v111, v4
	v_mov_b32_e32 v112, v4
	v_mov_b32_e32 v113, v4
	v_mov_b32_e32 v114, v4
	v_mov_b32_e32 v115, v4
	v_mov_b32_e32 v124, v4
	v_mov_b32_e32 v125, v4
	v_mov_b32_e32 v126, v4
	v_mov_b32_e32 v127, v4
	v_mov_b32_e32 v128, v4
	v_mov_b32_e32 v129, v4
	v_mov_b32_e32 v130, v4
	v_mov_b32_e32 v131, v4

.LBB0_2623:
	s_ashr_i32 s37, s36, 31
	s_lshl_b64 s[0:1], s[36:37], 19
	s_add_u32 s38, s30, s0
	s_addc_u32 s39, s31, s1
	s_and_b64 s[0:1], s[2:3], exec
	s_cselect_b32 s0, s39, s35
	s_cselect_b32 s1, s38, s34
	s_ashr_i32 s29, s28, 31
	s_lshl_b64 s[40:41], s[28:29], 19
	s_add_u32 s40, s6, s40
	s_addc_u32 s41, s7, s41
	s_and_b64 s[42:43], s[2:3], exec
	s_cselect_b32 s29, s41, s5
	s_cselect_b32 s37, s40, s4
	s_add_u32 s56, s4, 0x100
	s_addc_u32 s57, s5, 0
	s_add_u32 s4, s34, 0x40080
	v_mov_b32_e32 v4, 0
	s_addc_u32 s5, s35, 0
	s_mov_b32 s58, -2
	s_waitcnt lgkmcnt(0)
	v_mov_b32_e32 v5, v4
	v_mov_b32_e32 v6, v4
	v_mov_b32_e32 v7, v4
	v_mov_b32_e32 v8, v4
	v_mov_b32_e32 v9, v4
	v_mov_b32_e32 v10, v4
	v_mov_b32_e32 v11, v4
	v_mov_b32_e32 v20, v4
	v_mov_b32_e32 v21, v4
	v_mov_b32_e32 v22, v4
	v_mov_b32_e32 v23, v4
	v_mov_b32_e32 v24, v4
	v_mov_b32_e32 v25, v4
	v_mov_b32_e32 v26, v4
	v_mov_b32_e32 v27, v4
	v_mov_b32_e32 v36, v4
	v_mov_b32_e32 v37, v4
	v_mov_b32_e32 v38, v4
	v_mov_b32_e32 v39, v4
	v_mov_b32_e32 v40, v4
	v_mov_b32_e32 v41, v4
	v_mov_b32_e32 v42, v4
	v_mov_b32_e32 v43, v4
	v_mov_b32_e32 v52, v4
	v_mov_b32_e32 v53, v4
	v_mov_b32_e32 v54, v4
	v_mov_b32_e32 v55, v4
	v_mov_b32_e32 v56, v4
	v_mov_b32_e32 v57, v4
	v_mov_b32_e32 v58, v4
	v_mov_b32_e32 v59, v4
	v_mov_b32_e32 v12, v4
	v_mov_b32_e32 v13, v4
	v_mov_b32_e32 v14, v4
	v_mov_b32_e32 v15, v4
	v_mov_b32_e32 v16, v4
	v_mov_b32_e32 v17, v4
	v_mov_b32_e32 v18, v4
	v_mov_b32_e32 v19, v4
	v_mov_b32_e32 v28, v4
	v_mov_b32_e32 v29, v4
	v_mov_b32_e32 v30, v4
	v_mov_b32_e32 v31, v4
	v_mov_b32_e32 v32, v4
	v_mov_b32_e32 v33, v4
	v_mov_b32_e32 v34, v4
	v_mov_b32_e32 v35, v4
	v_mov_b32_e32 v44, v4
	v_mov_b32_e32 v45, v4
	v_mov_b32_e32 v46, v4
	v_mov_b32_e32 v47, v4
	v_mov_b32_e32 v48, v4
	v_mov_b32_e32 v49, v4
	v_mov_b32_e32 v50, v4
	v_mov_b32_e32 v51, v4
	v_mov_b32_e32 v60, v4
	v_mov_b32_e32 v61, v4
	v_mov_b32_e32 v62, v4
	v_mov_b32_e32 v63, v4
	v_mov_b32_e32 v64, v4
	v_mov_b32_e32 v65, v4
	v_mov_b32_e32 v66, v4
	v_mov_b32_e32 v67, v4
	v_mov_b32_e32 v68, v4
	v_mov_b32_e32 v69, v4
	v_mov_b32_e32 v70, v4
	v_mov_b32_e32 v71, v4
	v_mov_b32_e32 v72, v4
	v_mov_b32_e32 v73, v4
	v_mov_b32_e32 v74, v4
	v_mov_b32_e32 v75, v4
	v_mov_b32_e32 v84, v4
	v_mov_b32_e32 v85, v4
	v_mov_b32_e32 v86, v4
	v_mov_b32_e32 v87, v4
	v_mov_b32_e32 v88, v4
	v_mov_b32_e32 v89, v4
	v_mov_b32_e32 v90, v4
	v_mov_b32_e32 v91, v4
	v_mov_b32_e32 v100, v4
	v_mov_b32_e32 v101, v4
	v_mov_b32_e32 v102, v4
	v_mov_b32_e32 v103, v4
	v_mov_b32_e32 v104, v4
	v_mov_b32_e32 v105, v4
	v_mov_b32_e32 v106, v4
	v_mov_b32_e32 v107, v4
	v_mov_b32_e32 v116, v4
	v_mov_b32_e32 v117, v4
	v_mov_b32_e32 v118, v4
	v_mov_b32_e32 v119, v4
	v_mov_b32_e32 v120, v4
	v_mov_b32_e32 v121, v4
	v_mov_b32_e32 v122, v4
	v_mov_b32_e32 v123, v4
	v_mov_b32_e32 v76, v4
	v_mov_b32_e32 v77, v4
	v_mov_b32_e32 v78, v4
	v_mov_b32_e32 v79, v4
	v_mov_b32_e32 v80, v4
	v_mov_b32_e32 v81, v4
	v_mov_b32_e32 v82, v4
	v_mov_b32_e32 v83, v4
	v_mov_b32_e32 v92, v4
	v_mov_b32_e32 v93, v4
	v_mov_b32_e32 v94, v4
	v_mov_b32_e32 v95, v4
	v_mov_b32_e32 v96, v4
	v_mov_b32_e32 v97, v4
	v_mov_b32_e32 v98, v4
	v_mov_b32_e32 v99, v4
	v_mov_b32_e32 v108, v4
	v_mov_b32_e32 v109, v4
	v_mov_b32_e32 v110, v4
	v_mov_b32_e32 v111, v4
	v_mov_b32_e32 v112, v4
	v_mov_b32_e32 v113, v4
	v_mov_b32_e32 v114, v4
	v_mov_b32_e32 v115, v4
	v_mov_b32_e32 v124, v4
	v_mov_b32_e32 v125, v4
	v_mov_b32_e32 v126, v4
	v_mov_b32_e32 v127, v4
	v_mov_b32_e32 v128, v4
	v_mov_b32_e32 v129, v4
	v_mov_b32_e32 v130, v4
	v_mov_b32_e32 v131, v4

.LBB0_2649:
	v_ashrrev_i32_e32 v17, 31, v16
	v_lshlrev_b64 v[20:21], 11, v[16:17]
	v_lshl_add_u64 v[40:41], v[4:5], 0, v[20:21]
	global_load_dwordx4 v[44:47], v[40:41], off
	global_load_dwordx4 v[48:51], v[6:7], off
	global_load_dwordx4 v[52:55], v[8:9], off
	global_load_dwordx4 v[56:59], v[40:41], off offset:64
	global_load_dwordx4 v[60:63], v[6:7], off offset:64
	global_load_dwordx4 v[64:67], v[10:11], off
	global_load_dwordx4 v[68:71], v[40:41], off offset:128
	global_load_dwordx4 v[72:75], v[6:7], off offset:128
	global_load_dwordx4 v[76:79], v[12:13], off
	global_load_dwordx4 v[80:83], v[40:41], off offset:192
	global_load_dwordx4 v[84:87], v[6:7], off offset:192
	global_load_dwordx4 v[88:91], v[14:15], off
	s_add_i32 s1, s1, s10
	s_cmp_lt_i32 s1, 64
	s_waitcnt vmcnt(9)
	v_mfma_f32_16x16x32_bf16 v[24:27], v[48:51], v[44:47], 0
	v_mfma_f32_16x16x32_bf16 v[20:23], v[52:55], v[44:47], 0
	s_waitcnt vmcnt(6)
	v_mfma_f32_16x16x32_bf16 v[24:27], v[60:63], v[56:59], v[24:27]
	v_mfma_f32_16x16x32_bf16 v[20:23], v[64:67], v[56:59], v[20:23]
	s_waitcnt vmcnt(3)
	v_mfma_f32_16x16x32_bf16 v[24:27], v[72:75], v[68:71], v[24:27]
	v_mfma_f32_16x16x32_bf16 v[20:23], v[76:79], v[68:71], v[20:23]
	s_waitcnt vmcnt(0)
	v_mfma_f32_16x16x32_bf16 v[24:27], v[84:87], v[80:83], v[24:27]
	v_mfma_f32_16x16x32_bf16 v[20:23], v[88:91], v[80:83], v[20:23]
	s_nop 6
	ds_write_b128 v2, v[24:27]
	s_nop 0
	ds_write_b128 v2, v[20:23] offset:1024
	s_waitcnt lgkmcnt(0)
	s_barrier
	ds_read2st64_b32 v[20:21], v18 offset1:8
	s_waitcnt lgkmcnt(0)
	v_add_f32_e32 v17, 0, v20
	v_add_f32_e32 v17, v17, v21
	ds_read2st64_b32 v[20:21], v18 offset0:16 offset1:24
	s_waitcnt lgkmcnt(0)
	v_add_f32_e32 v17, v17, v20
	v_add_f32_e32 v17, v17, v21
	ds_read2st64_b32 v[20:21], v18 offset0:32 offset1:40
	s_waitcnt lgkmcnt(0)
	v_add_f32_e32 v17, v17, v20
	v_add_f32_e32 v17, v17, v21
	ds_read2st64_b32 v[20:21], v18 offset0:48 offset1:56
	s_waitcnt lgkmcnt(0)
	v_add_f32_e32 v17, v17, v20
	v_add_u32_e32 v20, v1, v16
	v_add_f32_e32 v17, v17, v21
	v_ashrrev_i32_e32 v21, 31, v20
	v_lshl_add_u64 v[20:21], v[20:21], 2, s[2:3]
	global_load_dword v19, v[20:21], off
	v_add_u32_e32 v16, s0, v16
	s_waitcnt vmcnt(0)
	v_add_f32_e32 v17, v17, v19
	global_store_dword v[20:21], v17, off
	s_barrier
	s_cbranch_scc1 .LBB0_2649

.LBB0_2715:
	s_ashr_i32 s37, s36, 31
	s_lshl_b64 s[0:1], s[36:37], 19
	s_add_u32 s38, s8, s0
	s_addc_u32 s39, s9, s1
	s_and_b64 s[0:1], s[2:3], exec
	s_cselect_b32 s0, s39, s5
	s_cselect_b32 s1, s38, s4
	s_ashr_i32 s29, s28, 31
	s_lshl_b64 s[40:41], s[28:29], 19
	s_add_u32 s40, s6, s40
	s_addc_u32 s41, s7, s41
	s_and_b64 s[42:43], s[2:3], exec
	s_cselect_b32 s29, s41, s35
	s_cselect_b32 s37, s40, s34
	s_add_u32 s4, s4, 0x40080
	s_addc_u32 s5, s5, 0
	s_add_u32 s56, s34, 0x100
	v_mov_b32_e32 v4, 0
	s_addc_u32 s57, s35, 0
	s_mov_b32 s58, -2
	v_mov_b32_e32 v5, v4
	v_mov_b32_e32 v6, v4
	v_mov_b32_e32 v7, v4
	v_mov_b32_e32 v8, v4
	v_mov_b32_e32 v9, v4
	v_mov_b32_e32 v10, v4
	v_mov_b32_e32 v11, v4
	v_mov_b32_e32 v20, v4
	v_mov_b32_e32 v21, v4
	v_mov_b32_e32 v22, v4
	v_mov_b32_e32 v23, v4
	v_mov_b32_e32 v24, v4
	v_mov_b32_e32 v25, v4
	v_mov_b32_e32 v26, v4
	v_mov_b32_e32 v27, v4
	v_mov_b32_e32 v36, v4
	v_mov_b32_e32 v37, v4
	v_mov_b32_e32 v38, v4
	v_mov_b32_e32 v39, v4
	v_mov_b32_e32 v40, v4
	v_mov_b32_e32 v41, v4
	v_mov_b32_e32 v42, v4
	v_mov_b32_e32 v43, v4
	v_mov_b32_e32 v52, v4
	v_mov_b32_e32 v53, v4
	v_mov_b32_e32 v54, v4
	v_mov_b32_e32 v55, v4
	v_mov_b32_e32 v56, v4
	v_mov_b32_e32 v57, v4
	v_mov_b32_e32 v58, v4
	v_mov_b32_e32 v59, v4
	v_mov_b32_e32 v12, v4
	v_mov_b32_e32 v13, v4
	v_mov_b32_e32 v14, v4
	v_mov_b32_e32 v15, v4
	v_mov_b32_e32 v16, v4
	v_mov_b32_e32 v17, v4
	v_mov_b32_e32 v18, v4
	v_mov_b32_e32 v19, v4
	v_mov_b32_e32 v28, v4
	v_mov_b32_e32 v29, v4
	v_mov_b32_e32 v30, v4
	v_mov_b32_e32 v31, v4
	v_mov_b32_e32 v32, v4
	v_mov_b32_e32 v33, v4
	v_mov_b32_e32 v34, v4
	v_mov_b32_e32 v35, v4
	v_mov_b32_e32 v44, v4
	v_mov_b32_e32 v45, v4
	v_mov_b32_e32 v46, v4
	v_mov_b32_e32 v47, v4
	v_mov_b32_e32 v48, v4
	v_mov_b32_e32 v49, v4
	v_mov_b32_e32 v50, v4
	v_mov_b32_e32 v51, v4
	v_mov_b32_e32 v60, v4
	v_mov_b32_e32 v61, v4
	v_mov_b32_e32 v62, v4
	v_mov_b32_e32 v63, v4
	v_mov_b32_e32 v64, v4
	v_mov_b32_e32 v65, v4
	v_mov_b32_e32 v66, v4
	v_mov_b32_e32 v67, v4
	v_mov_b32_e32 v68, v4
	v_mov_b32_e32 v69, v4
	v_mov_b32_e32 v70, v4
	v_mov_b32_e32 v71, v4
	v_mov_b32_e32 v72, v4
	v_mov_b32_e32 v73, v4
	v_mov_b32_e32 v74, v4
	v_mov_b32_e32 v75, v4
	v_mov_b32_e32 v84, v4
	v_mov_b32_e32 v85, v4
	v_mov_b32_e32 v86, v4
	v_mov_b32_e32 v87, v4
	v_mov_b32_e32 v88, v4
	v_mov_b32_e32 v89, v4
	v_mov_b32_e32 v90, v4
	v_mov_b32_e32 v91, v4
	v_mov_b32_e32 v100, v4
	v_mov_b32_e32 v101, v4
	v_mov_b32_e32 v102, v4
	v_mov_b32_e32 v103, v4
	v_mov_b32_e32 v104, v4
	v_mov_b32_e32 v105, v4
	v_mov_b32_e32 v106, v4
	v_mov_b32_e32 v107, v4
	v_mov_b32_e32 v116, v4
	v_mov_b32_e32 v117, v4
	v_mov_b32_e32 v118, v4
	v_mov_b32_e32 v119, v4
	v_mov_b32_e32 v120, v4
	v_mov_b32_e32 v121, v4
	v_mov_b32_e32 v122, v4
	v_mov_b32_e32 v123, v4
	v_mov_b32_e32 v76, v4
	v_mov_b32_e32 v77, v4
	v_mov_b32_e32 v78, v4
	v_mov_b32_e32 v79, v4
	v_mov_b32_e32 v80, v4
	v_mov_b32_e32 v81, v4
	v_mov_b32_e32 v82, v4
	v_mov_b32_e32 v83, v4
	v_mov_b32_e32 v92, v4
	v_mov_b32_e32 v93, v4
	v_mov_b32_e32 v94, v4
	v_mov_b32_e32 v95, v4
	v_mov_b32_e32 v96, v4
	v_mov_b32_e32 v97, v4
	v_mov_b32_e32 v98, v4
	v_mov_b32_e32 v99, v4
	v_mov_b32_e32 v108, v4
	v_mov_b32_e32 v109, v4
	v_mov_b32_e32 v110, v4
	v_mov_b32_e32 v111, v4
	v_mov_b32_e32 v112, v4
	v_mov_b32_e32 v113, v4
	v_mov_b32_e32 v114, v4
	v_mov_b32_e32 v115, v4
	v_mov_b32_e32 v124, v4
	v_mov_b32_e32 v125, v4
	v_mov_b32_e32 v126, v4
	v_mov_b32_e32 v127, v4
	v_mov_b32_e32 v128, v4
	v_mov_b32_e32 v129, v4
	v_mov_b32_e32 v130, v4
	v_mov_b32_e32 v131, v4

.LBB0_2799:
	s_ashr_i32 s29, s28, 31
	s_lshl_b64 s[0:1], s[28:29], 21
	s_add_u32 s36, s11, s0
	s_addc_u32 s37, s30, s1
	s_and_b64 s[0:1], s[2:3], exec
	s_cselect_b32 s0, s37, s35
	s_cselect_b32 s1, s36, s34
	s_ashr_i32 s27, s26, 31
	s_lshl_b64 s[38:39], s[26:27], 21
	s_add_u32 s38, s8, s38
	s_addc_u32 s39, s9, s39
	s_and_b64 s[40:41], s[2:3], exec
	s_cselect_b32 s27, s39, s5
	s_cselect_b32 s29, s38, s4
	s_add_u32 s54, s4, 0x100
	s_addc_u32 s55, s5, 0
	s_add_u32 s4, s34, 0x100080
	v_mov_b32_e32 v4, 0
	s_addc_u32 s5, s35, 0
	s_mov_b32 s56, -2
	s_waitcnt lgkmcnt(0)
	v_mov_b32_e32 v5, v4
	v_mov_b32_e32 v6, v4
	v_mov_b32_e32 v7, v4
	v_mov_b32_e32 v8, v4
	v_mov_b32_e32 v9, v4
	v_mov_b32_e32 v10, v4
	v_mov_b32_e32 v11, v4
	v_mov_b32_e32 v20, v4
	v_mov_b32_e32 v21, v4
	v_mov_b32_e32 v22, v4
	v_mov_b32_e32 v23, v4
	v_mov_b32_e32 v24, v4
	v_mov_b32_e32 v25, v4
	v_mov_b32_e32 v26, v4
	v_mov_b32_e32 v27, v4
	v_mov_b32_e32 v36, v4
	v_mov_b32_e32 v37, v4
	v_mov_b32_e32 v38, v4
	v_mov_b32_e32 v39, v4
	v_mov_b32_e32 v40, v4
	v_mov_b32_e32 v41, v4
	v_mov_b32_e32 v42, v4
	v_mov_b32_e32 v43, v4
	v_mov_b32_e32 v52, v4
	v_mov_b32_e32 v53, v4
	v_mov_b32_e32 v54, v4
	v_mov_b32_e32 v55, v4
	v_mov_b32_e32 v56, v4
	v_mov_b32_e32 v57, v4
	v_mov_b32_e32 v58, v4
	v_mov_b32_e32 v59, v4
	v_mov_b32_e32 v12, v4
	v_mov_b32_e32 v13, v4
	v_mov_b32_e32 v14, v4
	v_mov_b32_e32 v15, v4
	v_mov_b32_e32 v16, v4
	v_mov_b32_e32 v17, v4
	v_mov_b32_e32 v18, v4
	v_mov_b32_e32 v19, v4
	v_mov_b32_e32 v28, v4
	v_mov_b32_e32 v29, v4
	v_mov_b32_e32 v30, v4
	v_mov_b32_e32 v31, v4
	v_mov_b32_e32 v32, v4
	v_mov_b32_e32 v33, v4
	v_mov_b32_e32 v34, v4
	v_mov_b32_e32 v35, v4
	v_mov_b32_e32 v44, v4
	v_mov_b32_e32 v45, v4
	v_mov_b32_e32 v46, v4
	v_mov_b32_e32 v47, v4
	v_mov_b32_e32 v48, v4
	v_mov_b32_e32 v49, v4
	v_mov_b32_e32 v50, v4
	v_mov_b32_e32 v51, v4
	v_mov_b32_e32 v60, v4
	v_mov_b32_e32 v61, v4
	v_mov_b32_e32 v62, v4
	v_mov_b32_e32 v63, v4
	v_mov_b32_e32 v64, v4
	v_mov_b32_e32 v65, v4
	v_mov_b32_e32 v66, v4
	v_mov_b32_e32 v67, v4
	v_mov_b32_e32 v68, v4
	v_mov_b32_e32 v69, v4
	v_mov_b32_e32 v70, v4
	v_mov_b32_e32 v71, v4
	v_mov_b32_e32 v72, v4
	v_mov_b32_e32 v73, v4
	v_mov_b32_e32 v74, v4
	v_mov_b32_e32 v75, v4
	v_mov_b32_e32 v84, v4
	v_mov_b32_e32 v85, v4
	v_mov_b32_e32 v86, v4
	v_mov_b32_e32 v87, v4
	v_mov_b32_e32 v88, v4
	v_mov_b32_e32 v89, v4
	v_mov_b32_e32 v90, v4
	v_mov_b32_e32 v91, v4
	v_mov_b32_e32 v100, v4
	v_mov_b32_e32 v101, v4
	v_mov_b32_e32 v102, v4
	v_mov_b32_e32 v103, v4
	v_mov_b32_e32 v104, v4
	v_mov_b32_e32 v105, v4
	v_mov_b32_e32 v106, v4
	v_mov_b32_e32 v107, v4
	v_mov_b32_e32 v116, v4
	v_mov_b32_e32 v117, v4
	v_mov_b32_e32 v118, v4
	v_mov_b32_e32 v119, v4
	v_mov_b32_e32 v120, v4
	v_mov_b32_e32 v121, v4
	v_mov_b32_e32 v122, v4
	v_mov_b32_e32 v123, v4
	v_mov_b32_e32 v76, v4
	v_mov_b32_e32 v77, v4
	v_mov_b32_e32 v78, v4
	v_mov_b32_e32 v79, v4
	v_mov_b32_e32 v80, v4
	v_mov_b32_e32 v81, v4
	v_mov_b32_e32 v82, v4
	v_mov_b32_e32 v83, v4
	v_mov_b32_e32 v92, v4
	v_mov_b32_e32 v93, v4
	v_mov_b32_e32 v94, v4
	v_mov_b32_e32 v95, v4
	v_mov_b32_e32 v96, v4
	v_mov_b32_e32 v97, v4
	v_mov_b32_e32 v98, v4
	v_mov_b32_e32 v99, v4
	v_mov_b32_e32 v108, v4
	v_mov_b32_e32 v109, v4
	v_mov_b32_e32 v110, v4
	v_mov_b32_e32 v111, v4
	v_mov_b32_e32 v112, v4
	v_mov_b32_e32 v113, v4
	v_mov_b32_e32 v114, v4
	v_mov_b32_e32 v115, v4
	v_mov_b32_e32 v124, v4
	v_mov_b32_e32 v125, v4
	v_mov_b32_e32 v126, v4
	v_mov_b32_e32 v127, v4
	v_mov_b32_e32 v128, v4
	v_mov_b32_e32 v129, v4
	v_mov_b32_e32 v130, v4
	v_mov_b32_e32 v131, v4

.LBB0_2826:
	v_lshl_add_u64 v[34:35], v[22:23], 0, v[12:13]
	s_mov_b32 s5, 0x35d00000
	v_add_co_u32_e32 v40, vcc, s5, v34
	s_mov_b32 s5, 0x35d20000
	s_nop 0
	v_addc_co_u32_e32 v41, vcc, 0, v35, vcc
	v_add_co_u32_e32 v42, vcc, s5, v34
	s_nop 0
	v_addc_co_u32_e32 v43, vcc, 0, v35, vcc
	v_lshl_add_u64 v[38:39], v[20:21], 0, v[12:13]
	global_load_dwordx4 v[44:47], v[38:39], off
	global_load_dwordx4 v[48:51], v[40:41], off
	global_load_dwordx4 v[52:55], v[42:43], off
	global_load_dwordx4 v[56:59], v[38:39], off offset:64
	global_load_dwordx4 v[60:63], v[40:41], off offset:64
	global_load_dwordx4 v[64:67], v[42:43], off offset:64
	global_load_dwordx4 v[68:71], v[38:39], off offset:128
	global_load_dwordx4 v[72:75], v[40:41], off offset:128
	global_load_dwordx4 v[76:79], v[42:43], off offset:128
	global_load_dwordx4 v[80:83], v[38:39], off offset:192
	global_load_dwordx4 v[84:87], v[40:41], off offset:192
	global_load_dwordx4 v[88:91], v[42:43], off offset:192
	global_load_dwordx4 v[92:95], v[38:39], off offset:256
	global_load_dwordx4 v[96:99], v[40:41], off offset:256
	global_load_dwordx4 v[100:103], v[42:43], off offset:256
	global_load_dwordx4 v[104:107], v[38:39], off offset:320
	global_load_dwordx4 v[108:111], v[40:41], off offset:320
	global_load_dwordx4 v[112:115], v[42:43], off offset:320
	global_load_dwordx4 v[116:119], v[38:39], off offset:384
	global_load_dwordx4 v[120:123], v[40:41], off offset:384
	global_load_dwordx4 v[124:127], v[42:43], off offset:384
	global_load_dwordx4 v[128:131], v[38:39], off offset:448
	global_load_dwordx4 v[132:135], v[40:41], off offset:448
	global_load_dwordx4 v[136:139], v[42:43], off offset:448
	global_load_dwordx4 v[140:143], v[38:39], off offset:512
	global_load_dwordx4 v[144:147], v[40:41], off offset:512
	global_load_dwordx4 v[148:151], v[42:43], off offset:512
	global_load_dwordx4 v[152:155], v[38:39], off offset:576
	global_load_dwordx4 v[156:159], v[40:41], off offset:576
	global_load_dwordx4 v[160:163], v[42:43], off offset:576
	global_load_dwordx4 v[164:167], v[38:39], off offset:640
	global_load_dwordx4 v[168:171], v[40:41], off offset:640
	global_load_dwordx4 v[172:175], v[42:43], off offset:640
	global_load_dwordx4 v[176:179], v[38:39], off offset:704
	global_load_dwordx4 v[180:183], v[40:41], off offset:704
	global_load_dwordx4 v[184:187], v[42:43], off offset:704
	global_load_dwordx4 v[188:191], v[38:39], off offset:768
	global_load_dwordx4 v[192:195], v[40:41], off offset:768
	global_load_dwordx4 v[196:199], v[42:43], off offset:768
	global_load_dwordx4 v[200:203], v[38:39], off offset:832
	global_load_dwordx4 v[204:207], v[40:41], off offset:832
	global_load_dwordx4 v[208:211], v[42:43], off offset:832
	global_load_dwordx4 v[212:215], v[38:39], off offset:896
	global_load_dwordx4 v[216:219], v[40:41], off offset:896
	global_load_dwordx4 v[220:223], v[42:43], off offset:896
	global_load_dwordx4 v[224:227], v[38:39], off offset:960
	global_load_dwordx4 v[228:231], v[40:41], off offset:960
	global_load_dwordx4 v[232:235], v[42:43], off offset:960
	s_waitcnt vmcnt(45)
	v_mfma_f32_16x16x32_bf16 v[4:7], v[48:51], v[44:47], v[4:7]
	v_mfma_f32_16x16x32_bf16 v[8:11], v[52:55], v[44:47], v[8:11]
	s_waitcnt vmcnt(42)
	v_mfma_f32_16x16x32_bf16 v[4:7], v[60:63], v[56:59], v[4:7]
	v_mfma_f32_16x16x32_bf16 v[8:11], v[64:67], v[56:59], v[8:11]
	s_waitcnt vmcnt(39)
	v_mfma_f32_16x16x32_bf16 v[4:7], v[72:75], v[68:71], v[4:7]
	v_mfma_f32_16x16x32_bf16 v[8:11], v[76:79], v[68:71], v[8:11]
	s_waitcnt vmcnt(36)
	v_mfma_f32_16x16x32_bf16 v[4:7], v[84:87], v[80:83], v[4:7]
	v_mfma_f32_16x16x32_bf16 v[8:11], v[88:91], v[80:83], v[8:11]
	s_waitcnt vmcnt(33)
	v_mfma_f32_16x16x32_bf16 v[4:7], v[96:99], v[92:95], v[4:7]
	v_mfma_f32_16x16x32_bf16 v[8:11], v[100:103], v[92:95], v[8:11]
	s_waitcnt vmcnt(30)
	v_mfma_f32_16x16x32_bf16 v[4:7], v[108:111], v[104:107], v[4:7]
	v_mfma_f32_16x16x32_bf16 v[8:11], v[112:115], v[104:107], v[8:11]
	s_waitcnt vmcnt(27)
	v_mfma_f32_16x16x32_bf16 v[4:7], v[120:123], v[116:119], v[4:7]
	v_mfma_f32_16x16x32_bf16 v[8:11], v[124:127], v[116:119], v[8:11]
	s_waitcnt vmcnt(24)
	v_mfma_f32_16x16x32_bf16 v[4:7], v[132:135], v[128:131], v[4:7]
	v_mfma_f32_16x16x32_bf16 v[8:11], v[136:139], v[128:131], v[8:11]
	s_waitcnt vmcnt(21)
	v_mfma_f32_16x16x32_bf16 v[4:7], v[144:147], v[140:143], v[4:7]
	v_mfma_f32_16x16x32_bf16 v[8:11], v[148:151], v[140:143], v[8:11]
	s_waitcnt vmcnt(18)
	v_mfma_f32_16x16x32_bf16 v[4:7], v[156:159], v[152:155], v[4:7]
	v_mfma_f32_16x16x32_bf16 v[8:11], v[160:163], v[152:155], v[8:11]
	s_waitcnt vmcnt(15)
	v_mfma_f32_16x16x32_bf16 v[4:7], v[168:171], v[164:167], v[4:7]
	v_mfma_f32_16x16x32_bf16 v[8:11], v[172:175], v[164:167], v[8:11]
	s_waitcnt vmcnt(12)
	v_mfma_f32_16x16x32_bf16 v[4:7], v[180:183], v[176:179], v[4:7]
	v_mfma_f32_16x16x32_bf16 v[8:11], v[184:187], v[176:179], v[8:11]
	s_waitcnt vmcnt(9)
	v_mfma_f32_16x16x32_bf16 v[4:7], v[192:195], v[188:191], v[4:7]
	v_mfma_f32_16x16x32_bf16 v[8:11], v[196:199], v[188:191], v[8:11]
	s_waitcnt vmcnt(6)
	v_mfma_f32_16x16x32_bf16 v[4:7], v[204:207], v[200:203], v[4:7]
	v_mfma_f32_16x16x32_bf16 v[8:11], v[208:211], v[200:203], v[8:11]
	s_waitcnt vmcnt(3)
	v_mfma_f32_16x16x32_bf16 v[4:7], v[216:219], v[212:215], v[4:7]
	v_mfma_f32_16x16x32_bf16 v[8:11], v[220:223], v[212:215], v[8:11]
	s_waitcnt vmcnt(0)
	v_mfma_f32_16x16x32_bf16 v[4:7], v[228:231], v[224:227], v[4:7]
	v_mfma_f32_16x16x32_bf16 v[8:11], v[232:235], v[224:227], v[8:11]
	s_nop 7
	ds_write_b128 v2, v[4:7]
	s_nop 0
	ds_write_b128 v2, v[8:11] offset:1024
	s_waitcnt lgkmcnt(0)
	s_barrier
	ds_read2st64_b32 v[4:5], v25 offset1:8
	v_lshl_or_b32 v19, s1, 4, v1
	s_add_i32 s1, s1, s10
	v_add_u32_e32 v18, s0, v18
	s_cmp_gt_i32 s1, 63
	s_waitcnt lgkmcnt(0)
	v_add_f32_e32 v4, 0, v4
	v_add_f32_e32 v6, v4, v5
	ds_read2st64_b32 v[4:5], v25 offset0:16 offset1:24
	s_waitcnt lgkmcnt(0)
	v_add_f32_e32 v4, v6, v4
	v_add_f32_e32 v6, v4, v5
	ds_read2st64_b32 v[4:5], v25 offset0:32 offset1:40
	s_waitcnt lgkmcnt(0)
	v_add_f32_e32 v4, v6, v4
	v_add_f32_e32 v6, v4, v5
	ds_read2st64_b32 v[4:5], v25 offset0:48 offset1:56
	s_waitcnt lgkmcnt(0)
	v_add_f32_e32 v4, v6, v4
	v_add_f32_e32 v6, v4, v5
	v_add_u32_e32 v4, v19, v24
	v_ashrrev_i32_e32 v5, 31, v4
	v_lshl_add_u64 v[4:5], v[4:5], 2, s[2:3]
	global_load_dword v7, v[4:5], off
	s_waitcnt vmcnt(0)
	v_add_f32_e32 v6, v6, v7
	global_store_dword v[4:5], v6, off
	s_barrier
	s_cbranch_scc0 .LBB0_2825
